# grid syncs 2-10 replaced by monotonic-counter barrier in unused d_ws space (no-return atomic arrive, sc1 poll), first sync still cooperative-groups; on top of v26
# speedup vs baseline: 1.0257x; 1.0057x over previous
; #define RUNPH(n, body)                                   \
;   if (DUP_PH == (n) && DUP_PH == 10) { phase10<true>(p, smem, bid, nb); __syncthreads(); } \
;   if (PHON(n) && lo <= (n) && (n) < hi) { for (int rep = 0; rep < ((DUP_PH == (n) && DUP_PH != 10) ? hi - 9 : 1); rep++) { body; __syncthreads(); } }         \
;   if (lo <= (n) && (n) + 1 < hi) cg::this_grid().sync();
; DI void phase0(const P& p, char* smem, int bid, int nb) {
;   const int tid = threadIdx.x, lane = tid & 63, w = tid >> 6;
;   u16* XN = (u16*)p.out;
;   float* BETA = (float*)(p.ws + WS_BETA);
;   float* G = (float*)(p.ws + WS_G);
;   float* Wt = (float*)smem;
;   for (int i = tid; i < 4096; i += NT) {
; __global__ void __launch_bounds__(NT) mega(P p, int lo, int hi) {
;   extern __shared__ __attribute__((aligned(16))) char smem[];
;   const int bid = blockIdx.x, nb = gridDim.x;
;     ...
;   RUNPH(0, phase0(p, smem, bid, nb))
_Z4mega1Pii:
	s_load_dwordx2 s[4:5], s[0:1], 0xd8
	s_load_dwordx8 s[20:27], s[0:1], 0x0
	s_load_dwordx4 s[28:31], s[0:1], 0x38
	s_load_dwordx16 s[36:51], s[0:1], 0x98
	v_writelane_b32 v251, s2, 0
	s_add_u32 s2, s0, 0xe0
	s_addc_u32 s3, s1, 0
	s_waitcnt lgkmcnt(0)
	s_load_dword s98, s[0:1], 0xe0
	s_mov_b32 s99, 0
	v_readlane_b32 s100, v251, 0
	s_cmp_lg_u32 s100, 0
	s_cbranch_scc1 .Lgs_noinit
	v_and_b32_e32 v2, 0x3ff, v0
	v_cmp_eq_u32_e32 vcc, 0, v2
	s_add_u32 s100, s50, 0x3940000
	s_addc_u32 s101, s51, 0
	v_mov_b32_e32 v2, 0
	v_mov_b32_e32 v3, 0
	s_and_saveexec_b64 vcc, vcc
	s_cbranch_execz .Lgs_initdone
	global_atomic_swap v2, v3, s[100:101]
	s_waitcnt vmcnt(0)
.Lgs_initdone:
	s_mov_b64 exec, vcc
.Lgs_noinit:
	s_waitcnt lgkmcnt(0)
	v_writelane_b32 v251, s36, 1
	s_cmp_lt_i32 s4, 1
	s_cselect_b64 s[8:9], -1, 0
	v_writelane_b32 v251, s37, 2
	v_writelane_b32 v251, s38, 3
	v_writelane_b32 v251, s39, 4
	v_writelane_b32 v251, s40, 5
	v_writelane_b32 v251, s41, 6
	v_writelane_b32 v251, s42, 7
	v_writelane_b32 v251, s43, 8
	v_writelane_b32 v251, s44, 9
	v_writelane_b32 v251, s45, 10
	v_writelane_b32 v251, s46, 11
	v_writelane_b32 v251, s47, 12
	v_writelane_b32 v251, s48, 13
	v_writelane_b32 v251, s49, 14
	v_writelane_b32 v251, s50, 15
	v_writelane_b32 v251, s51, 16
	v_writelane_b32 v251, s2, 17
	s_cmp_gt_i32 s4, 0
	s_nop 0
	v_writelane_b32 v251, s3, 18
	s_load_dword s2, s[0:1], 0xe0
	s_waitcnt lgkmcnt(0)
	v_writelane_b32 v251, s2, 19
	s_nop 1
	v_writelane_b32 v251, s3, 20
	s_cselect_b64 s[2:3], -1, 0
	v_writelane_b32 v251, s4, 21
	s_cmp_lt_i32 s5, 1
	s_nop 0
	v_writelane_b32 v251, s5, 22
	s_cselect_b64 s[4:5], -1, 0
	s_or_b64 s[2:3], s[2:3], s[4:5]
	s_and_b64 vcc, exec, s[2:3]
	s_cbranch_vccnz .LBB0_29
	v_and_b32_e32 v2, 3, v0
	v_and_b32_e32 v3, 0x1fc, v0
	s_load_dwordx2 s[12:13], s[0:1], 0x30
	s_load_dwordx4 s[4:7], s[0:1], 0x48
	v_bfe_u32 v6, v0, 2, 8
	v_lshl_or_b32 v3, v2, 14, v3
	v_add_u32_e32 v5, 0, v3
	v_mul_hi_u32_u24_e32 v3, 0x9040, v6
	v_mul_u32_u24_e32 v6, 0x9040, v6
	v_lshl_or_b32 v2, v2, 4, v6
	v_and_b32_e32 v4, 0x3ff, v0
	v_lshl_add_u64 v[2:3], s[28:29], 0, v[2:3]
	s_mov_b64 s[2:3], 0x4000
	v_or_b32_e32 v1, 0xfffffe00, v4
	v_lshl_add_u64 v[2:3], v[2:3], 0, s[2:3]
	s_mov_b64 s[2:3], 0
	s_mov_b64 s[10:11], 0x482000
	s_movk_i32 s14, 0xdff

.LBB0_109:
	s_load_dwordx2 s[2:3], s[0:1], 0xd8
	s_waitcnt lgkmcnt(0)
	s_cmp_gt_i32 s3, 2
	s_cselect_b64 s[2:3], -1, 0
	s_and_b64 s[4:5], s[4:5], s[2:3]
	s_andn2_b64 vcc, exec, s[4:5]
	s_cbranch_vccnz .LBB0_121
	v_and_b32_e32 v1, 0x3fffffff, v0
	v_cmp_eq_u32_e32 vcc, 0, v1
	s_barrier
	s_add_i32 s99, s99, 1
	s_and_saveexec_b64 s[4:5], vcc
	s_cbranch_execz .Lgs1_done
	v_readlane_b32 s6, v251, 15
	v_readlane_b32 s7, v251, 16
	s_add_u32 s6, s6, 0x3940000
	s_addc_u32 s7, s7, 0
	buffer_wbl2 sc1
	s_waitcnt vmcnt(0)
	v_mov_b32_e32 v1, 0
	v_mov_b32_e32 v2, 1
	global_atomic_add v1, v2, s[6:7]
	s_mul_i32 s8, s99, s98
.Lgs1_poll:
	global_load_dword v2, v1, s[6:7] sc1
	s_waitcnt vmcnt(0)
	v_readfirstlane_b32 s9, v2
	s_cmp_ge_u32 s9, s8
	s_cbranch_scc1 .Lgs1_arrived
	s_sleep 2
	s_branch .Lgs1_poll

.LBB0_321:
	s_load_dwordx16 s[4:19], s[0:1], 0x58
	s_waitcnt lgkmcnt(0)
	v_writelane_b32 v251, s4, 29
	s_nop 1
	v_writelane_b32 v251, s5, 30
	v_writelane_b32 v251, s6, 31
	v_writelane_b32 v251, s7, 32
	v_writelane_b32 v251, s8, 33
	v_writelane_b32 v251, s9, 34
	v_writelane_b32 v251, s10, 35
	v_writelane_b32 v251, s11, 36
	v_writelane_b32 v251, s12, 37
	v_writelane_b32 v251, s13, 38
	v_writelane_b32 v251, s14, 39
	v_writelane_b32 v251, s15, 40
	v_writelane_b32 v251, s16, 41
	v_writelane_b32 v251, s17, 42
	v_writelane_b32 v251, s18, 43
	v_writelane_b32 v251, s19, 44
	s_nop 0
	v_readlane_b32 s0, v251, 21
	v_readlane_b32 s1, v251, 22
	s_cmp_gt_i32 s1, 3
	s_cselect_b64 s[0:1], -1, 0
	s_and_b64 s[2:3], s[28:29], s[0:1]
	s_andn2_b64 vcc, exec, s[2:3]
	s_cbranch_vccnz .LBB0_333
	v_and_b32_e32 v1, 0x3fffffff, v0
	v_cmp_eq_u32_e32 vcc, 0, v1
	s_barrier
	s_add_i32 s99, s99, 1
	s_and_saveexec_b64 s[2:3], vcc
	s_cbranch_execz .Lgs2_done
	v_readlane_b32 s4, v251, 15
	v_readlane_b32 s5, v251, 16
	s_add_u32 s4, s4, 0x3940000
	s_addc_u32 s5, s5, 0
	buffer_wbl2 sc1
	s_waitcnt vmcnt(0)
	v_mov_b32_e32 v1, 0
	v_mov_b32_e32 v2, 1
	global_atomic_add v1, v2, s[4:5]
	s_mul_i32 s6, s99, s98
.Lgs2_poll:
	global_load_dword v2, v1, s[4:5] sc1
	s_waitcnt vmcnt(0)
	v_readfirstlane_b32 s7, v2
	s_cmp_ge_u32 s7, s6
	s_cbranch_scc1 .Lgs2_arrived
	s_sleep 2
	s_branch .Lgs2_poll

.LBB0_528:
	v_readlane_b32 s0, v251, 21
	v_readlane_b32 s1, v251, 22
	s_cmp_gt_i32 s1, 4
	s_cselect_b64 s[0:1], -1, 0
	s_and_b64 s[2:3], s[18:19], s[0:1]
	s_andn2_b64 vcc, exec, s[2:3]
	s_cbranch_vccnz .LBB0_540
	v_and_b32_e32 v1, 0x3fffffff, v0
	v_cmp_eq_u32_e32 vcc, 0, v1
	s_barrier
	s_add_i32 s99, s99, 1
	s_and_saveexec_b64 s[2:3], vcc
	s_cbranch_execz .Lgs3_done
	v_readlane_b32 s4, v251, 15
	v_readlane_b32 s5, v251, 16
	s_add_u32 s4, s4, 0x3940000
	s_addc_u32 s5, s5, 0
	buffer_wbl2 sc1
	s_waitcnt vmcnt(0)
	v_mov_b32_e32 v1, 0
	v_mov_b32_e32 v2, 1
	global_atomic_add v1, v2, s[4:5]
	s_mul_i32 s6, s99, s98

.LBB0_718:
	v_readlane_b32 s0, v251, 21
	v_readlane_b32 s1, v251, 22
	s_cmp_gt_i32 s1, 5
	s_cselect_b64 s[0:1], -1, 0
	s_and_b64 s[2:3], s[6:7], s[0:1]
	s_andn2_b64 vcc, exec, s[2:3]
	s_cbranch_vccnz .LBB0_730
	v_and_b32_e32 v1, 0x3fffffff, v0
	v_cmp_eq_u32_e32 vcc, 0, v1
	s_barrier
	s_add_i32 s99, s99, 1
	s_and_saveexec_b64 s[2:3], vcc
	s_cbranch_execz .Lgs4_done
	v_readlane_b32 s4, v251, 15
	v_readlane_b32 s5, v251, 16
	s_add_u32 s4, s4, 0x3940000
	s_addc_u32 s5, s5, 0
	buffer_wbl2 sc1
	s_waitcnt vmcnt(0)
	v_mov_b32_e32 v1, 0
	v_mov_b32_e32 v2, 1
	global_atomic_add v1, v2, s[4:5]
	s_mul_i32 s6, s99, s98

.LBB0_789:
	v_readlane_b32 s0, v251, 21
	v_readlane_b32 s1, v251, 22
	s_cmp_gt_i32 s1, 6
	s_cselect_b64 s[0:1], -1, 0
	s_and_b64 s[2:3], s[2:3], s[0:1]
	s_andn2_b64 vcc, exec, s[2:3]
	s_cbranch_vccnz .LBB0_801
	v_and_b32_e32 v2, 0x3fffffff, v0
	v_cmp_eq_u32_e32 vcc, 0, v2
	s_barrier
	s_add_i32 s99, s99, 1
	s_and_saveexec_b64 s[2:3], vcc
	s_cbranch_execz .Lgs5_done
	v_readlane_b32 s4, v251, 15
	v_readlane_b32 s5, v251, 16
	s_add_u32 s4, s4, 0x3940000
	s_addc_u32 s5, s5, 0
	buffer_wbl2 sc1
	s_waitcnt vmcnt(0)
	v_mov_b32_e32 v2, 0
	v_mov_b32_e32 v3, 1
	global_atomic_add v2, v3, s[4:5]
	s_mul_i32 s6, s99, s98
.Lgs5_poll:
	global_load_dword v3, v2, s[4:5] sc1
	s_waitcnt vmcnt(0)
	v_readfirstlane_b32 s7, v3
	s_cmp_ge_u32 s7, s6
	s_cbranch_scc1 .Lgs5_arrived
	s_sleep 2
	s_branch .Lgs5_poll

.LBB0_811:
	v_readlane_b32 s0, v251, 21
	v_readlane_b32 s1, v251, 22
	s_cmp_gt_i32 s1, 7
	s_cselect_b64 s[2:3], -1, 0
	s_and_b64 s[0:1], s[4:5], s[2:3]
	s_andn2_b64 vcc, exec, s[0:1]
	s_cbranch_vccnz .LBB0_823
	v_and_b32_e32 v2, 0x3fffffff, v0
	v_cmp_eq_u32_e32 vcc, 0, v2
	s_barrier
	s_add_i32 s99, s99, 1
	s_and_saveexec_b64 s[0:1], vcc
	s_cbranch_execz .Lgs6_done
	v_readlane_b32 s4, v251, 15
	v_readlane_b32 s5, v251, 16
	s_add_u32 s4, s4, 0x3940000
	s_addc_u32 s5, s5, 0
	buffer_wbl2 sc1
	s_waitcnt vmcnt(0)
	v_mov_b32_e32 v2, 0
	v_mov_b32_e32 v3, 1
	global_atomic_add v2, v3, s[4:5]
	s_mul_i32 s6, s99, s98

.LBB0_849:
	v_readlane_b32 s2, v251, 21
	v_readlane_b32 s3, v251, 22
	s_cmp_gt_i32 s3, 8
	s_cselect_b64 s[2:3], -1, 0
	s_and_b64 s[0:1], s[0:1], s[2:3]
	s_andn2_b64 vcc, exec, s[0:1]
	s_cbranch_vccnz .LBB0_861
	v_and_b32_e32 v2, 0x3fffffff, v0
	v_cmp_eq_u32_e32 vcc, 0, v2
	s_barrier
	s_add_i32 s99, s99, 1
	s_and_saveexec_b64 s[0:1], vcc
	s_cbranch_execz .Lgs7_done
	v_readlane_b32 s4, v251, 15
	v_readlane_b32 s5, v251, 16
	s_add_u32 s4, s4, 0x3940000
	s_addc_u32 s5, s5, 0
	buffer_wbl2 sc1
	s_waitcnt vmcnt(0)
	v_mov_b32_e32 v2, 0
	v_mov_b32_e32 v3, 1
	global_atomic_add v2, v3, s[4:5]
	s_mul_i32 s6, s99, s98

.LBB0_866:
	v_readlane_b32 s2, v251, 21
	v_readlane_b32 s3, v251, 22
	s_cmp_gt_i32 s3, 9
	s_cselect_b64 s[2:3], -1, 0
	s_and_b64 s[0:1], s[0:1], s[2:3]
	s_andn2_b64 vcc, exec, s[0:1]
	s_cbranch_vccnz .LBB0_878
	v_and_b32_e32 v2, 0x3fffffff, v0
	v_cmp_eq_u32_e32 vcc, 0, v2
	s_barrier
	s_add_i32 s99, s99, 1
	s_and_saveexec_b64 s[0:1], vcc
	s_cbranch_execz .Lgs8_done
	v_readlane_b32 s4, v251, 15
	v_readlane_b32 s5, v251, 16
	s_add_u32 s4, s4, 0x3940000
	s_addc_u32 s5, s5, 0
	buffer_wbl2 sc1
	s_waitcnt vmcnt(0)
	v_mov_b32_e32 v2, 0
	v_mov_b32_e32 v3, 1
	global_atomic_add v2, v3, s[4:5]
	s_mul_i32 s6, s99, s98

.LBB0_900:
	v_readlane_b32 s0, v251, 21
	v_readlane_b32 s1, v251, 22
	s_cmp_gt_i32 s1, 10
	s_cselect_b64 s[0:1], -1, 0
	s_and_b64 s[2:3], s[4:5], s[0:1]
	s_andn2_b64 vcc, exec, s[2:3]
	s_cbranch_vccnz .LBB0_912
	v_and_b32_e32 v2, 0x3fffffff, v0
	v_cmp_eq_u32_e32 vcc, 0, v2
	s_barrier
	s_add_i32 s99, s99, 1
	s_and_saveexec_b64 s[2:3], vcc
	s_cbranch_execz .Lgs9_done
	v_readlane_b32 s4, v251, 15
	v_readlane_b32 s5, v251, 16
	s_add_u32 s4, s4, 0x3940000
	s_addc_u32 s5, s5, 0
	buffer_wbl2 sc1
	s_waitcnt vmcnt(0)
	v_mov_b32_e32 v2, 0
	v_mov_b32_e32 v3, 1
	global_atomic_add v2, v3, s[4:5]
	s_mul_i32 s6, s99, s98
